# P5 epilogue: dead SSQ address chains removed, ACT stores with scalar base + one v_mad_u32_u24 offset each instead of v_mad_i64_i32 + three 64-bit adds
# baseline (speedup 1.0000x reference)
; __device__ __forceinline__ float sigm(float x) { return __builtin_amdgcn_rcpf(1.0f + __expf(-x)); }
; __device__ __forceinline__ u32x4 pack8_bf16(const float (&o)[8]) { u32x4 w; w.x = cvt_pk_bf16(o[0], o[1]); w.y = cvt_pk_bf16(o[2], o[3]); w.z = cvt_pk_bf16(o[4], o[5]); w.w = cvt_pk_bf16(o[6], o[7]); return w; }
;     __device__ __forceinline__ void operator()(const f32x4 (&acc)[2][2][4][2], const Unit& u, int wr, int wc, int fr, int fq) const {
;         const int row0 = u.pm * BM + wr * 64 + fr;
;         f32x4 sq[2][4];
; #pragma unroll
;         for (int ai = 0; ai < 2; ++ai)
; #pragma unroll
;             for (int m = 0; m < 4; ++m) sq[ai][m] = *(const f32x4*)(SSQ + (size_t)(row0 + ai * HALF + m * 16) * 16 + 4 * fq);
; #pragma unroll
;         for (int ai = 0; ai < 2; ++ai)
; #pragma unroll
;             for (int m = 0; m < 4; ++m) {
;                 const int row = row0 + ai * HALF + m * 16;
;                 float ss = (sq[ai][m][0] + sq[ai][m][1]) + (sq[ai][m][2] + sq[ai][m][3]);
;                 ss += __shfl_xor(ss, 16); ss += __shfl_xor(ss, 32);
;                 const float rstd = __builtin_amdgcn_rsqf(ss * (1.0f / 1024.0f) + 1e-6f);
;                 float o[8];
; #pragma unroll
;                 for (int k = 0; k < 8; ++k) { const float g = acc[ai][0][m][k >> 2][k & 3] * rstd, up = acc[ai][1][m][k >> 2][k & 3] * rstd; o[k] = g * sigm(g) * up; }
;                 *(u32x4*)(ACT + (size_t)row * 2816 + u.pn * 128 + wc * 32 + 8 * fq) = pack8_bf16(o);
.Lmy_ssq_have:
	v_lshl_add_u32 v186, s22, 8, v189
	v_or_b32_e32 v184, 16, v186
	v_or_b32_e32 v182, 32, v186
	v_add_u32_e32 v178, 0x80, v186
	v_add_u32_e32 v176, 0x90, v186
	v_add_u32_e32 v174, 0xa0, v186
	v_or_b32_e32 v180, 48, v186
	v_add_u32_e32 v172, 0xb0, v186
	s_lshl_b32 s22, s23, 7
	s_ashr_i32 s23, s22, 31
	s_lshl_b64 s[22:23], s[22:23], 1
	s_add_u32 s96, s8, s22
	s_addc_u32 s97, s9, s23
	s_add_u32 s96, s96, s4
	s_addc_u32 s97, s97, s5
	s_andn2_b64 vcc, exec, s[2:3]
	s_mov_b64 s[2:3], -1
	s_nop 0
	v_mov_b32_e32 v198, v236
	v_pk_mul_f32 v[124:125], v[124:125], v[198:199] op_sel_hi:[1,0]
	v_pk_mul_f32 v[120:121], v[120:121], v[198:199] op_sel_hi:[1,0]
	v_pk_mul_f32 v[122:123], v[122:123], v[198:199] op_sel_hi:[1,0]
	v_pk_mul_f32 v[116:117], v[116:117], v[198:199] op_sel_hi:[1,0]
	v_pk_mul_f32 v[126:127], v[126:127], v[198:199] op_sel_hi:[1,0]
	v_pk_mul_f32 v[118:119], v[118:119], v[198:199] op_sel_hi:[1,0]
	v_pk_mul_f32 v[112:113], v[112:113], v[198:199] op_sel_hi:[1,0]
	v_pk_mul_f32 v[114:115], v[114:115], v[198:199] op_sel_hi:[1,0]
	v_mul_f32_e32 v181, 0xbfb8aa3b, v124
	v_mul_f32_e32 v183, 0xbfb8aa3b, v125
	v_mul_f32_e32 v196, 0xbfb8aa3b, v120
	v_mul_f32_e32 v197, 0xbfb8aa3b, v121
	v_mul_f32_e32 v198, 0xbfb8aa3b, v122
	v_mul_f32_e32 v199, 0xbfb8aa3b, v123
	v_exp_f32_e32 v181, v181
	v_exp_f32_e32 v183, v183
	v_exp_f32_e32 v196, v196
	v_exp_f32_e32 v197, v197
	v_exp_f32_e32 v198, v198
	v_exp_f32_e32 v199, v199
	v_add_f32_e32 v181, 1.0, v181
	v_add_f32_e32 v183, 1.0, v183
	v_add_f32_e32 v200, 1.0, v196
	v_add_f32_e32 v201, 1.0, v197
	v_add_f32_e32 v202, 1.0, v198
	v_add_f32_e32 v203, 1.0, v199
	v_rcp_f32_e32 v196, v181
	v_rcp_f32_e32 v197, v183
	v_rcp_f32_e32 v200, v200
	v_rcp_f32_e32 v201, v201
	v_rcp_f32_e32 v202, v202
	v_rcp_f32_e32 v203, v203
	v_pk_mul_f32 v[124:125], v[124:125], v[196:197]
	v_pk_mul_f32 v[120:121], v[120:121], v[200:201]
	v_pk_mul_f32 v[122:123], v[122:123], v[202:203]
	v_pk_mul_f32 v[116:117], v[116:117], v[124:125]
	v_pk_mul_f32 v[112:113], v[112:113], v[120:121]
	v_pk_mul_f32 v[120:121], v[114:115], v[122:123]
	v_cvt_pk_bf16_f32 v114, v116, v117
	v_cvt_pk_bf16_f32 v117, v120, v121
	v_mul_f32_e32 v185, 0xbfb8aa3b, v126
	v_mul_f32_e32 v187, 0xbfb8aa3b, v127
	v_exp_f32_e32 v185, v185
	v_exp_f32_e32 v187, v187
	v_add_f32_e32 v185, 1.0, v185
	v_add_f32_e32 v187, 1.0, v187
	v_rcp_f32_e32 v198, v185
	v_rcp_f32_e32 v199, v187
	v_mov_b32_e32 v120, v237
	v_cvt_pk_bf16_f32 v116, v112, v113
	v_pk_mul_f32 v[126:127], v[126:127], v[198:199]
	v_pk_mul_f32 v[108:109], v[108:109], v[120:121] op_sel_hi:[1,0]
	v_pk_mul_f32 v[118:119], v[118:119], v[126:127]
	v_mul_f32_e32 v121, 0xbfb8aa3b, v108
	v_cvt_pk_bf16_f32 v115, v118, v119
	v_mad_u32_u24 v118, v186, s49, v160
	v_exp_f32_e32 v121, v121
	global_store_dwordx4 v118, v[114:117], s[96:97]
	v_pk_mul_f32 v[110:111], v[110:111], v[120:121] op_sel_hi:[1,0]
	v_pk_mul_f32 v[100:101], v[100:101], v[120:121] op_sel_hi:[1,0]
	v_mul_f32_e32 v114, 0xbfb8aa3b, v109
	v_exp_f32_e32 v115, v114
	v_mul_f32_e32 v116, 0xbfb8aa3b, v110
	v_mul_f32_e32 v117, 0xbfb8aa3b, v111
	v_exp_f32_e32 v116, v116
	v_exp_f32_e32 v117, v117
	v_add_f32_e32 v114, 1.0, v121
	v_add_f32_e32 v115, 1.0, v115
	v_rcp_f32_e32 v114, v114
	v_rcp_f32_e32 v115, v115
	v_add_f32_e32 v116, 1.0, v116
	v_add_f32_e32 v117, 1.0, v117
	v_rcp_f32_e32 v116, v116
	v_rcp_f32_e32 v117, v117
	v_pk_mul_f32 v[108:109], v[108:109], v[114:115]
	v_pk_mul_f32 v[102:103], v[102:103], v[120:121] op_sel_hi:[1,0]
	v_pk_mul_f32 v[100:101], v[100:101], v[108:109]
	v_pk_mul_f32 v[108:109], v[110:111], v[116:117]
	v_pk_mul_f32 v[104:105], v[104:105], v[120:121] op_sel_hi:[1,0]
	v_pk_mul_f32 v[102:103], v[102:103], v[108:109]
	v_mul_f32_e32 v110, 0xbfb8aa3b, v104
	v_mul_f32_e32 v108, 0xbfb8aa3b, v105
	v_exp_f32_e32 v110, v110
	v_exp_f32_e32 v109, v108
	v_pk_mul_f32 v[106:107], v[106:107], v[120:121] op_sel_hi:[1,0]
	v_pk_mul_f32 v[96:97], v[96:97], v[120:121] op_sel_hi:[1,0]
	v_add_f32_e32 v108, 1.0, v110
	v_add_f32_e32 v109, 1.0, v109
	v_mul_f32_e32 v110, 0xbfb8aa3b, v106
	v_mul_f32_e32 v111, 0xbfb8aa3b, v107
	v_rcp_f32_e32 v108, v108
	v_rcp_f32_e32 v109, v109
	v_exp_f32_e32 v110, v110
	v_exp_f32_e32 v111, v111
	v_pk_mul_f32 v[104:105], v[104:105], v[108:109]
	v_add_f32_e32 v108, 1.0, v110
	v_add_f32_e32 v109, 1.0, v111
	v_rcp_f32_e32 v108, v108
	v_rcp_f32_e32 v109, v109
	v_pk_mul_f32 v[104:105], v[96:97], v[104:105]
	v_pk_mul_f32 v[96:97], v[98:99], v[120:121] op_sel_hi:[1,0]
	v_pk_mul_f32 v[98:99], v[106:107], v[108:109]
	v_pk_mul_f32 v[106:107], v[96:97], v[98:99]
	v_cvt_pk_bf16_f32 v96, v100, v101
	v_cvt_pk_bf16_f32 v98, v104, v105
	v_cvt_pk_bf16_f32 v97, v102, v103
	v_mov_b32_e32 v100, v238
	v_mad_u32_u24 v102, v184, s49, v160
	v_pk_mul_f32 v[92:93], v[92:93], v[100:101] op_sel_hi:[1,0]
	v_mul_f32_e32 v101, 0xbfb8aa3b, v92
	v_exp_f32_e32 v101, v101
	v_mul_f32_e32 v104, 0xbfb8aa3b, v93
	v_exp_f32_e32 v105, v104
	v_cvt_pk_bf16_f32 v99, v106, v107
	v_add_f32_e32 v101, 1.0, v101
	v_rcp_f32_e32 v104, v101
	v_add_f32_e32 v101, 1.0, v105
	v_rcp_f32_e32 v105, v101
	v_pk_mul_f32 v[94:95], v[94:95], v[100:101] op_sel_hi:[1,0]
	global_store_dwordx4 v102, v[96:99], s[96:97]
	v_pk_mul_f32 v[88:89], v[88:89], v[100:101] op_sel_hi:[1,0]
	v_pk_mul_f32 v[92:93], v[92:93], v[104:105]
	v_mul_f32_e32 v96, 0xbfb8aa3b, v94
	v_exp_f32_e32 v96, v96
	v_pk_mul_f32 v[88:89], v[88:89], v[92:93]
	v_mul_f32_e32 v92, 0xbfb8aa3b, v95
	v_exp_f32_e32 v93, v92
	v_pk_mul_f32 v[84:85], v[84:85], v[100:101] op_sel_hi:[1,0]
	v_add_f32_e32 v92, 1.0, v96
	v_mul_f32_e32 v96, 0xbfb8aa3b, v84
	v_mul_f32_e32 v97, 0xbfb8aa3b, v85
	v_exp_f32_e32 v96, v96
	v_exp_f32_e32 v97, v97
	v_add_f32_e32 v93, 1.0, v93
; __device__ __forceinline__ float sigm(float x) { return __builtin_amdgcn_rcpf(1.0f + __expf(-x)); }
; __device__ __forceinline__ u32x4 pack8_bf16(const float (&o)[8]) { u32x4 w; w.x = cvt_pk_bf16(o[0], o[1]); w.y = cvt_pk_bf16(o[2], o[3]); w.z = cvt_pk_bf16(o[4], o[5]); w.w = cvt_pk_bf16(o[6], o[7]); return w; }
;     __device__ __forceinline__ void operator()(const f32x4 (&acc)[2][2][4][2], const Unit& u, int wr, int wc, int fr, int fq) const {
;     ...
;         for (int ai = 0; ai < 2; ++ai)
; #pragma unroll
;             for (int m = 0; m < 4; ++m) {
;                 const int row = row0 + ai * HALF + m * 16;
;                 float ss = (sq[ai][m][0] + sq[ai][m][1]) + (sq[ai][m][2] + sq[ai][m][3]);
;                 ss += __shfl_xor(ss, 16); ss += __shfl_xor(ss, 32);
;                 const float rstd = __builtin_amdgcn_rsqf(ss * (1.0f / 1024.0f) + 1e-6f);
;                 float o[8];
; #pragma unroll
;                 for (int k = 0; k < 8; ++k) { const float g = acc[ai][0][m][k >> 2][k & 3] * rstd, up = acc[ai][1][m][k >> 2][k & 3] * rstd; o[k] = g * sigm(g) * up; }
;                 *(u32x4*)(ACT + (size_t)row * 2816 + u.pn * 128 + wc * 32 + 8 * fq) = pack8_bf16(o);
	v_rcp_f32_e32 v92, v92
	v_rcp_f32_e32 v93, v93
	v_add_f32_e32 v96, 1.0, v96
	v_add_f32_e32 v97, 1.0, v97
	v_rcp_f32_e32 v96, v96
	v_rcp_f32_e32 v97, v97
	v_pk_mul_f32 v[90:91], v[90:91], v[100:101] op_sel_hi:[1,0]
	v_pk_mul_f32 v[92:93], v[94:95], v[92:93]
	v_pk_mul_f32 v[86:87], v[86:87], v[100:101] op_sel_hi:[1,0]
	v_pk_mul_f32 v[90:91], v[90:91], v[92:93]
	v_mul_f32_e32 v92, 0xbfb8aa3b, v86
	v_pk_mul_f32 v[80:81], v[80:81], v[100:101] op_sel_hi:[1,0]
	v_pk_mul_f32 v[84:85], v[84:85], v[96:97]
	v_exp_f32_e32 v92, v92
	v_pk_mul_f32 v[84:85], v[80:81], v[84:85]
	v_mul_f32_e32 v80, 0xbfb8aa3b, v87
	v_exp_f32_e32 v81, v80
	v_add_f32_e32 v80, 1.0, v92
	v_add_f32_e32 v81, 1.0, v81
	v_rcp_f32_e32 v80, v80
	v_rcp_f32_e32 v81, v81
	v_pk_mul_f32 v[82:83], v[82:83], v[100:101] op_sel_hi:[1,0]
	v_pk_mul_f32 v[80:81], v[86:87], v[80:81]
	s_nop 0
	v_pk_mul_f32 v[86:87], v[82:83], v[80:81]
	v_cvt_pk_bf16_f32 v80, v88, v89
	v_cvt_pk_bf16_f32 v83, v86, v87
	v_cvt_pk_bf16_f32 v82, v84, v85
	v_mad_u32_u24 v84, v182, s49, v160
	v_mov_b32_e32 v86, v239
	v_cvt_pk_bf16_f32 v81, v90, v91
	v_pk_mul_f32 v[76:77], v[76:77], v[86:87] op_sel_hi:[1,0]
	v_mul_f32_e32 v87, 0xbfb8aa3b, v76
	v_exp_f32_e32 v87, v87
	global_store_dwordx4 v84, v[80:83], s[96:97]
	v_pk_mul_f32 v[78:79], v[78:79], v[86:87] op_sel_hi:[1,0]
	s_nop 0
	v_mul_f32_e32 v80, 0xbfb8aa3b, v77
	v_exp_f32_e32 v81, v80
	v_mul_f32_e32 v82, 0xbfb8aa3b, v78
	v_mul_f32_e32 v83, 0xbfb8aa3b, v79
	v_exp_f32_e32 v82, v82
	v_exp_f32_e32 v83, v83
	v_add_f32_e32 v80, 1.0, v87
	v_add_f32_e32 v81, 1.0, v81
	v_rcp_f32_e32 v80, v80
	v_rcp_f32_e32 v81, v81
	v_add_f32_e32 v82, 1.0, v82
	v_add_f32_e32 v83, 1.0, v83
	v_rcp_f32_e32 v82, v82
	v_rcp_f32_e32 v83, v83
	v_pk_mul_f32 v[68:69], v[68:69], v[86:87] op_sel_hi:[1,0]
	v_pk_mul_f32 v[76:77], v[76:77], v[80:81]
	v_pk_mul_f32 v[70:71], v[70:71], v[86:87] op_sel_hi:[1,0]
	v_pk_mul_f32 v[68:69], v[68:69], v[76:77]
	v_pk_mul_f32 v[76:77], v[78:79], v[82:83]
	v_pk_mul_f32 v[72:73], v[72:73], v[86:87] op_sel_hi:[1,0]
	v_pk_mul_f32 v[70:71], v[70:71], v[76:77]
	v_mul_f32_e32 v78, 0xbfb8aa3b, v72
	v_mul_f32_e32 v76, 0xbfb8aa3b, v73
	v_exp_f32_e32 v78, v78
	v_exp_f32_e32 v77, v76
	v_pk_mul_f32 v[74:75], v[74:75], v[86:87] op_sel_hi:[1,0]
	v_pk_mul_f32 v[64:65], v[64:65], v[86:87] op_sel_hi:[1,0]
	v_add_f32_e32 v76, 1.0, v78
	v_add_f32_e32 v77, 1.0, v77
	v_mul_f32_e32 v78, 0xbfb8aa3b, v74
	v_mul_f32_e32 v79, 0xbfb8aa3b, v75
	v_rcp_f32_e32 v76, v76
	v_rcp_f32_e32 v77, v77
	v_exp_f32_e32 v78, v78
	v_exp_f32_e32 v79, v79
	v_pk_mul_f32 v[72:73], v[72:73], v[76:77]
	v_add_f32_e32 v76, 1.0, v78
	v_add_f32_e32 v77, 1.0, v79
	v_rcp_f32_e32 v76, v76
	v_rcp_f32_e32 v77, v77
	v_pk_mul_f32 v[72:73], v[64:65], v[72:73]
	v_pk_mul_f32 v[64:65], v[66:67], v[86:87] op_sel_hi:[1,0]
	v_pk_mul_f32 v[66:67], v[74:75], v[76:77]
	v_pk_mul_f32 v[74:75], v[64:65], v[66:67]
	v_cvt_pk_bf16_f32 v64, v68, v69
	v_cvt_pk_bf16_f32 v66, v72, v73
	v_cvt_pk_bf16_f32 v65, v70, v71
	v_mov_b32_e32 v68, v240
	v_mad_u32_u24 v70, v180, s49, v160
	v_pk_mul_f32 v[60:61], v[60:61], v[68:69] op_sel_hi:[1,0]
	v_mul_f32_e32 v69, 0xbfb8aa3b, v60
	v_exp_f32_e32 v69, v69
	v_mul_f32_e32 v72, 0xbfb8aa3b, v61
	v_exp_f32_e32 v73, v72
	v_cvt_pk_bf16_f32 v67, v74, v75
	v_add_f32_e32 v69, 1.0, v69
	v_rcp_f32_e32 v72, v69
	v_add_f32_e32 v69, 1.0, v73
	v_rcp_f32_e32 v73, v69
	v_pk_mul_f32 v[62:63], v[62:63], v[68:69] op_sel_hi:[1,0]
	global_store_dwordx4 v70, v[64:67], s[96:97]
	v_pk_mul_f32 v[56:57], v[56:57], v[68:69] op_sel_hi:[1,0]
	v_pk_mul_f32 v[60:61], v[60:61], v[72:73]
	v_mul_f32_e32 v64, 0xbfb8aa3b, v62
	v_exp_f32_e32 v64, v64
	v_pk_mul_f32 v[56:57], v[56:57], v[60:61]
	v_mul_f32_e32 v60, 0xbfb8aa3b, v63
	v_exp_f32_e32 v61, v60
	v_pk_mul_f32 v[52:53], v[52:53], v[68:69] op_sel_hi:[1,0]
	v_add_f32_e32 v60, 1.0, v64
	v_mul_f32_e32 v64, 0xbfb8aa3b, v52
	v_mul_f32_e32 v65, 0xbfb8aa3b, v53
	v_exp_f32_e32 v64, v64
	v_exp_f32_e32 v65, v65
	v_add_f32_e32 v61, 1.0, v61
	v_rcp_f32_e32 v60, v60
	v_rcp_f32_e32 v61, v61
	v_add_f32_e32 v64, 1.0, v64
	v_add_f32_e32 v65, 1.0, v65
	v_rcp_f32_e32 v64, v64
	v_rcp_f32_e32 v65, v65
	v_pk_mul_f32 v[58:59], v[58:59], v[68:69] op_sel_hi:[1,0]
	v_pk_mul_f32 v[60:61], v[62:63], v[60:61]
	v_pk_mul_f32 v[54:55], v[54:55], v[68:69] op_sel_hi:[1,0]
	v_pk_mul_f32 v[58:59], v[58:59], v[60:61]
	v_mul_f32_e32 v60, 0xbfb8aa3b, v54
	v_pk_mul_f32 v[48:49], v[48:49], v[68:69] op_sel_hi:[1,0]
	v_pk_mul_f32 v[52:53], v[52:53], v[64:65]
	v_exp_f32_e32 v60, v60
	v_pk_mul_f32 v[52:53], v[48:49], v[52:53]
	v_mul_f32_e32 v48, 0xbfb8aa3b, v55
	v_exp_f32_e32 v49, v48
	v_add_f32_e32 v48, 1.0, v60
	v_add_f32_e32 v49, 1.0, v49
	v_rcp_f32_e32 v48, v48
	v_rcp_f32_e32 v49, v49
	v_pk_mul_f32 v[50:51], v[50:51], v[68:69] op_sel_hi:[1,0]
	v_pk_mul_f32 v[48:49], v[54:55], v[48:49]
	s_nop 0
	v_pk_mul_f32 v[54:55], v[50:51], v[48:49]
	v_cvt_pk_bf16_f32 v48, v56, v57
	v_cvt_pk_bf16_f32 v51, v54, v55
	v_cvt_pk_bf16_f32 v50, v52, v53
	v_mad_u32_u24 v52, v178, s49, v160
	v_mov_b32_e32 v54, v241
	v_cvt_pk_bf16_f32 v49, v58, v59
	v_pk_mul_f32 v[44:45], v[44:45], v[54:55] op_sel_hi:[1,0]
	v_mul_f32_e32 v55, 0xbfb8aa3b, v44
	v_exp_f32_e32 v55, v55
	global_store_dwordx4 v52, v[48:51], s[96:97]
	v_pk_mul_f32 v[46:47], v[46:47], v[54:55] op_sel_hi:[1,0]
	s_nop 0
	v_mul_f32_e32 v48, 0xbfb8aa3b, v45
	v_exp_f32_e32 v49, v48
	v_mul_f32_e32 v50, 0xbfb8aa3b, v46
	v_mul_f32_e32 v51, 0xbfb8aa3b, v47
	v_exp_f32_e32 v50, v50
	v_exp_f32_e32 v51, v51
	v_add_f32_e32 v48, 1.0, v55
	v_add_f32_e32 v49, 1.0, v49
	v_rcp_f32_e32 v48, v48
; __device__ __forceinline__ float sigm(float x) { return __builtin_amdgcn_rcpf(1.0f + __expf(-x)); }
; __device__ __forceinline__ u32x4 pack8_bf16(const float (&o)[8]) { u32x4 w; w.x = cvt_pk_bf16(o[0], o[1]); w.y = cvt_pk_bf16(o[2], o[3]); w.z = cvt_pk_bf16(o[4], o[5]); w.w = cvt_pk_bf16(o[6], o[7]); return w; }
;     __device__ __forceinline__ void operator()(const f32x4 (&acc)[2][2][4][2], const Unit& u, int wr, int wc, int fr, int fq) const {
;     ...
;         for (int ai = 0; ai < 2; ++ai)
; #pragma unroll
;             for (int m = 0; m < 4; ++m) {
;                 const int row = row0 + ai * HALF + m * 16;
;                 float ss = (sq[ai][m][0] + sq[ai][m][1]) + (sq[ai][m][2] + sq[ai][m][3]);
;                 ss += __shfl_xor(ss, 16); ss += __shfl_xor(ss, 32);
;                 const float rstd = __builtin_amdgcn_rsqf(ss * (1.0f / 1024.0f) + 1e-6f);
;                 float o[8];
; #pragma unroll
;                 for (int k = 0; k < 8; ++k) { const float g = acc[ai][0][m][k >> 2][k & 3] * rstd, up = acc[ai][1][m][k >> 2][k & 3] * rstd; o[k] = g * sigm(g) * up; }
;                 *(u32x4*)(ACT + (size_t)row * 2816 + u.pn * 128 + wc * 32 + 8 * fq) = pack8_bf16(o);
	v_rcp_f32_e32 v49, v49
	v_add_f32_e32 v50, 1.0, v50
	v_add_f32_e32 v51, 1.0, v51
	v_rcp_f32_e32 v50, v50
	v_rcp_f32_e32 v51, v51
	v_pk_mul_f32 v[36:37], v[36:37], v[54:55] op_sel_hi:[1,0]
	v_pk_mul_f32 v[44:45], v[44:45], v[48:49]
	v_pk_mul_f32 v[38:39], v[38:39], v[54:55] op_sel_hi:[1,0]
	v_pk_mul_f32 v[36:37], v[36:37], v[44:45]
	v_pk_mul_f32 v[44:45], v[46:47], v[50:51]
	v_pk_mul_f32 v[40:41], v[40:41], v[54:55] op_sel_hi:[1,0]
	v_pk_mul_f32 v[38:39], v[38:39], v[44:45]
	v_mul_f32_e32 v46, 0xbfb8aa3b, v40
	v_mul_f32_e32 v44, 0xbfb8aa3b, v41
	v_exp_f32_e32 v46, v46
	v_exp_f32_e32 v45, v44
	v_pk_mul_f32 v[42:43], v[42:43], v[54:55] op_sel_hi:[1,0]
	v_pk_mul_f32 v[32:33], v[32:33], v[54:55] op_sel_hi:[1,0]
	v_add_f32_e32 v44, 1.0, v46
	v_add_f32_e32 v45, 1.0, v45
	v_mul_f32_e32 v46, 0xbfb8aa3b, v42
	v_mul_f32_e32 v47, 0xbfb8aa3b, v43
	v_rcp_f32_e32 v44, v44
	v_rcp_f32_e32 v45, v45
	v_exp_f32_e32 v46, v46
	v_exp_f32_e32 v47, v47
	v_pk_mul_f32 v[40:41], v[40:41], v[44:45]
	v_add_f32_e32 v44, 1.0, v46
	v_add_f32_e32 v45, 1.0, v47
	v_rcp_f32_e32 v44, v44
	v_rcp_f32_e32 v45, v45
	v_pk_mul_f32 v[40:41], v[32:33], v[40:41]
	v_pk_mul_f32 v[32:33], v[34:35], v[54:55] op_sel_hi:[1,0]
	v_pk_mul_f32 v[34:35], v[42:43], v[44:45]
	v_pk_mul_f32 v[42:43], v[32:33], v[34:35]
	v_cvt_pk_bf16_f32 v32, v36, v37
	v_cvt_pk_bf16_f32 v34, v40, v41
	v_cvt_pk_bf16_f32 v33, v38, v39
	v_mov_b32_e32 v36, v242
	v_mad_u32_u24 v38, v176, s49, v160
	v_pk_mul_f32 v[28:29], v[28:29], v[36:37] op_sel_hi:[1,0]
	v_mul_f32_e32 v37, 0xbfb8aa3b, v28
	v_exp_f32_e32 v37, v37
	v_mul_f32_e32 v40, 0xbfb8aa3b, v29
	v_exp_f32_e32 v41, v40
	v_cvt_pk_bf16_f32 v35, v42, v43
	v_add_f32_e32 v37, 1.0, v37
	v_rcp_f32_e32 v40, v37
	v_add_f32_e32 v37, 1.0, v41
	v_rcp_f32_e32 v41, v37
	v_pk_mul_f32 v[30:31], v[30:31], v[36:37] op_sel_hi:[1,0]
	global_store_dwordx4 v38, v[32:35], s[96:97]
	v_pk_mul_f32 v[24:25], v[24:25], v[36:37] op_sel_hi:[1,0]
	v_pk_mul_f32 v[28:29], v[28:29], v[40:41]
	v_mul_f32_e32 v32, 0xbfb8aa3b, v30
	v_exp_f32_e32 v32, v32
	v_pk_mul_f32 v[24:25], v[24:25], v[28:29]
	v_mul_f32_e32 v28, 0xbfb8aa3b, v31
	v_exp_f32_e32 v29, v28
	v_pk_mul_f32 v[20:21], v[20:21], v[36:37] op_sel_hi:[1,0]
	v_add_f32_e32 v28, 1.0, v32
	v_mul_f32_e32 v32, 0xbfb8aa3b, v20
	v_mul_f32_e32 v33, 0xbfb8aa3b, v21
	v_exp_f32_e32 v32, v32
	v_exp_f32_e32 v33, v33
	v_add_f32_e32 v29, 1.0, v29
	v_rcp_f32_e32 v28, v28
	v_rcp_f32_e32 v29, v29
	v_add_f32_e32 v32, 1.0, v32
	v_add_f32_e32 v33, 1.0, v33
	v_rcp_f32_e32 v32, v32
	v_rcp_f32_e32 v33, v33
	v_pk_mul_f32 v[26:27], v[26:27], v[36:37] op_sel_hi:[1,0]
	v_pk_mul_f32 v[28:29], v[30:31], v[28:29]
	v_pk_mul_f32 v[22:23], v[22:23], v[36:37] op_sel_hi:[1,0]
	v_pk_mul_f32 v[26:27], v[26:27], v[28:29]
	v_mul_f32_e32 v28, 0xbfb8aa3b, v22
	v_pk_mul_f32 v[16:17], v[16:17], v[36:37] op_sel_hi:[1,0]
	v_pk_mul_f32 v[20:21], v[20:21], v[32:33]
	v_exp_f32_e32 v28, v28
	v_pk_mul_f32 v[20:21], v[16:17], v[20:21]
	v_mul_f32_e32 v16, 0xbfb8aa3b, v23
	v_exp_f32_e32 v17, v16
	v_add_f32_e32 v16, 1.0, v28
	v_add_f32_e32 v17, 1.0, v17
	v_rcp_f32_e32 v16, v16
	v_rcp_f32_e32 v17, v17
	v_pk_mul_f32 v[18:19], v[18:19], v[36:37] op_sel_hi:[1,0]
	v_pk_mul_f32 v[16:17], v[22:23], v[16:17]
	s_nop 0
	v_pk_mul_f32 v[22:23], v[18:19], v[16:17]
	v_cvt_pk_bf16_f32 v16, v24, v25
	v_cvt_pk_bf16_f32 v19, v22, v23
	v_cvt_pk_bf16_f32 v18, v20, v21
	v_mad_u32_u24 v20, v174, s49, v160
	v_mov_b32_e32 v22, v243
	v_cvt_pk_bf16_f32 v17, v26, v27
	v_pk_mul_f32 v[12:13], v[12:13], v[22:23] op_sel_hi:[1,0]
	v_mul_f32_e32 v23, 0xbfb8aa3b, v12
	v_exp_f32_e32 v23, v23
	global_store_dwordx4 v20, v[16:19], s[96:97]
	v_pk_mul_f32 v[14:15], v[14:15], v[22:23] op_sel_hi:[1,0]
	s_nop 0
	v_mul_f32_e32 v16, 0xbfb8aa3b, v13
	v_exp_f32_e32 v17, v16
	v_mul_f32_e32 v18, 0xbfb8aa3b, v14
	v_mul_f32_e32 v19, 0xbfb8aa3b, v15
	v_exp_f32_e32 v18, v18
	v_exp_f32_e32 v19, v19
	v_add_f32_e32 v16, 1.0, v23
	v_add_f32_e32 v17, 1.0, v17
	v_rcp_f32_e32 v16, v16
	v_rcp_f32_e32 v17, v17
	v_add_f32_e32 v18, 1.0, v18
	v_add_f32_e32 v19, 1.0, v19
	v_rcp_f32_e32 v18, v18
	v_rcp_f32_e32 v19, v19
	v_pk_mul_f32 v[4:5], v[4:5], v[22:23] op_sel_hi:[1,0]
	v_pk_mul_f32 v[12:13], v[12:13], v[16:17]
	v_pk_mul_f32 v[8:9], v[8:9], v[22:23] op_sel_hi:[1,0]
	v_pk_mul_f32 v[4:5], v[4:5], v[12:13]
	v_pk_mul_f32 v[12:13], v[14:15], v[18:19]
	v_mul_f32_e32 v14, 0xbfb8aa3b, v8
	v_exp_f32_e32 v14, v14
	v_pk_mul_f32 v[6:7], v[6:7], v[22:23] op_sel_hi:[1,0]
	v_pk_mul_f32 v[10:11], v[10:11], v[22:23] op_sel_hi:[1,0]
	v_pk_mul_f32 v[6:7], v[6:7], v[12:13]
	v_mul_f32_e32 v12, 0xbfb8aa3b, v9
	v_exp_f32_e32 v13, v12
	v_add_f32_e32 v12, 1.0, v14
	v_mul_f32_e32 v14, 0xbfb8aa3b, v10
	v_mul_f32_e32 v15, 0xbfb8aa3b, v11
	v_exp_f32_e32 v14, v14
	v_exp_f32_e32 v15, v15
	v_add_f32_e32 v13, 1.0, v13
	v_rcp_f32_e32 v12, v12
	v_rcp_f32_e32 v13, v13
	v_add_f32_e32 v14, 1.0, v14
	v_add_f32_e32 v15, 1.0, v15
	v_rcp_f32_e32 v14, v14
	v_rcp_f32_e32 v15, v15
	v_pk_mul_f32 v[0:1], v[0:1], v[22:23] op_sel_hi:[1,0]
	v_pk_mul_f32 v[8:9], v[8:9], v[12:13]
	s_nop 0
	v_pk_mul_f32 v[8:9], v[0:1], v[8:9]
	v_pk_mul_f32 v[0:1], v[2:3], v[22:23] op_sel_hi:[1,0]
	v_pk_mul_f32 v[2:3], v[10:11], v[14:15]
	s_nop 0
	v_pk_mul_f32 v[10:11], v[0:1], v[2:3]
	v_cvt_pk_bf16_f32 v0, v4, v5
	v_mad_u32_u24 v4, v172, s49, v160
	v_cvt_pk_bf16_f32 v1, v6, v7
	v_cvt_pk_bf16_f32 v2, v8, v9
	v_cvt_pk_bf16_f32 v3, v10, v11
	global_store_dwordx4 v4, v[0:3], s[96:97]
	s_cbranch_vccnz .LBB0_965
	s_andn2_b64 vcc, exec, s[6:7]
	s_cbranch_vccnz .LBB0_964
	s_barrier
	s_branch .LBB0_964
